# second input projection K-loop: first K-tile after an epilogue peeled, its two counted waits exclude the epilogue's 16 stores (vmcnt 24)
# baseline (speedup 1.0000x reference)
.LBB0_477:
	s_or_b64 exec, exec, s[6:7]
	v_readlane_b32 s4, v253, 2
	v_readlane_b32 s5, v253, 3
	s_mov_b64 s[0:1], s[4:5]
	s_waitcnt lgkmcnt(0)
	s_barrier
	s_mov_b32 s19, 0
	s_load_dwordx2 s[6:7], s[0:1], 0x78
	s_mov_b64 s[0:1], s[4:5]
	s_load_dwordx2 s[28:29], s[0:1], 0x78
	s_mov_b64 s[0:1], s[4:5]
	s_load_dwordx2 s[30:31], s[0:1], 0x78
	s_mov_b64 s[0:1], s[4:5]
	s_load_dwordx2 s[34:35], s[0:1], 0x78
	s_mov_b64 s[0:1], s[4:5]
	s_load_dwordx2 s[10:11], s[0:1], 0x78
	s_mov_b64 s[0:1], s[4:5]
	s_load_dwordx2 s[12:13], s[0:1], 0x78
	s_mov_b64 s[0:1], s[4:5]
	s_load_dwordx2 s[26:27], s[0:1], 0x78
	s_mov_b64 s[0:1], s[4:5]
	s_load_dwordx2 s[16:17], s[0:1], 0x78
	s_mov_b64 s[0:1], s[4:5]
	v_mov_b32_e32 v0, 0x20008
	s_load_dwordx2 s[14:15], s[0:1], 0x78
	v_mov_b32_e32 v8, v236
	v_add_u32_e32 v0, 0, v0
	ds_read_b32 v0, v0
	s_mov_b64 s[38:39], -1
	v_readfirstlane_b32 s40, v8
	s_waitcnt lgkmcnt(0)
	v_readfirstlane_b32 s0, v0
	s_ashr_i32 s1, s0, 31
	s_cmpk_gt_i32 s0, 0x3ff
	s_cbranch_scc0 .LBB0_480
	s_and_b32 s2, s0, 0x7fffff00
	s_mov_b64 s[38:39], 0
	s_cmpk_lg_i32 s2, 0x400
	s_mov_b64 s[36:37], 0
	s_cbranch_scc1 .LBB0_480
	s_lshr_b32 s2, s0, 3
	s_and_b32 s2, s2, 28
	s_lshl_b32 s4, s0, 5
	s_or_b32 s2, s2, s4
	s_bfe_u32 s42, s0, 0x20003
	s_bfe_u32 s50, s2, 0x60002
	s_mov_b64 s[4:5], 0
	s_mov_b32 s67, 1
	s_mov_b64 s[36:37], -1

.LBB0_497:
	s_ashr_i32 s35, s34, 31
	s_lshl_b64 s[26:27], s[34:35], 19
	s_cmp_eq_u32 s66, 0
	s_cselect_b32 s35, s2, s55
	s_cselect_b32 s31, s52, s58
	s_cselect_b32 s48, s53, s59
	s_cselect_b32 s49, s54, s92
	s_add_u32 s44, s35, s26
	s_addc_u32 s45, s31, s27
	s_and_b64 s[26:27], s[36:37], exec
	s_cselect_b32 s35, s45, s5
	s_cselect_b32 s43, s44, s4
	s_ashr_i32 s31, s30, 31
	s_lshl_b64 s[26:27], s[30:31], 19
	s_add_u32 s48, s48, s26
	s_addc_u32 s49, s49, s27
	s_and_b64 s[26:27], s[36:37], exec
	s_cselect_b32 s31, s49, s47
	s_cselect_b32 vcc_lo, s48, s46
	s_add_u32 s26, s4, 0x40080
	s_addc_u32 s27, s5, 0
	s_add_u32 vcc_hi, s46, 0x100
	v_mov_b32_e32 v0, 0
	s_addc_u32 s68, s47, 0
	s_mov_b32 s69, -2
	v_mov_b32_e32 v1, v0
	v_mov_b32_e32 v2, v0
	v_mov_b32_e32 v3, v0
	v_mov_b32_e32 v4, v0
	v_mov_b32_e32 v5, v0
	v_mov_b32_e32 v6, v0
	v_mov_b32_e32 v7, v0
	v_mov_b32_e32 v16, v0
	v_mov_b32_e32 v17, v0
	v_mov_b32_e32 v18, v0
	v_mov_b32_e32 v19, v0
	v_mov_b32_e32 v20, v0
	v_mov_b32_e32 v21, v0
	v_mov_b32_e32 v22, v0
	v_mov_b32_e32 v23, v0
	v_mov_b32_e32 v32, v0
	v_mov_b32_e32 v33, v0
	v_mov_b32_e32 v34, v0
	v_mov_b32_e32 v35, v0
	v_mov_b32_e32 v36, v0
	v_mov_b32_e32 v37, v0
	v_mov_b32_e32 v38, v0
	v_mov_b32_e32 v39, v0
	v_mov_b32_e32 v48, v0
	v_mov_b32_e32 v49, v0
	v_mov_b32_e32 v50, v0
	v_mov_b32_e32 v51, v0
	v_mov_b32_e32 v52, v0
	v_mov_b32_e32 v53, v0
	v_mov_b32_e32 v54, v0
	v_mov_b32_e32 v55, v0
	v_mov_b32_e32 v8, v0
	v_mov_b32_e32 v9, v0
	v_mov_b32_e32 v10, v0
	v_mov_b32_e32 v11, v0
	v_mov_b32_e32 v12, v0
	v_mov_b32_e32 v13, v0
	v_mov_b32_e32 v14, v0
	v_mov_b32_e32 v15, v0
	v_mov_b32_e32 v24, v0
	v_mov_b32_e32 v25, v0
	v_mov_b32_e32 v26, v0
	v_mov_b32_e32 v27, v0
	v_mov_b32_e32 v28, v0
	v_mov_b32_e32 v29, v0
	v_mov_b32_e32 v30, v0
	v_mov_b32_e32 v31, v0
	v_mov_b32_e32 v40, v0
	v_mov_b32_e32 v41, v0
	v_mov_b32_e32 v42, v0
	v_mov_b32_e32 v43, v0
	v_mov_b32_e32 v44, v0
	v_mov_b32_e32 v45, v0
	v_mov_b32_e32 v46, v0
	v_mov_b32_e32 v47, v0
	v_mov_b32_e32 v56, v0
	v_mov_b32_e32 v57, v0
	v_mov_b32_e32 v58, v0
	v_mov_b32_e32 v59, v0
	v_mov_b32_e32 v60, v0
	v_mov_b32_e32 v61, v0
	v_mov_b32_e32 v62, v0
	v_mov_b32_e32 v63, v0
	v_mov_b32_e32 v64, v0
	v_mov_b32_e32 v65, v0
	v_mov_b32_e32 v66, v0
	v_mov_b32_e32 v67, v0
	v_mov_b32_e32 v68, v0
	v_mov_b32_e32 v69, v0
	v_mov_b32_e32 v70, v0
	v_mov_b32_e32 v71, v0
	v_mov_b32_e32 v80, v0
	v_mov_b32_e32 v81, v0
	v_mov_b32_e32 v82, v0
	v_mov_b32_e32 v83, v0
	v_mov_b32_e32 v84, v0
	v_mov_b32_e32 v85, v0
	v_mov_b32_e32 v86, v0
	v_mov_b32_e32 v87, v0
	v_mov_b32_e32 v96, v0
	v_mov_b32_e32 v97, v0
	v_mov_b32_e32 v98, v0
	v_mov_b32_e32 v99, v0
	v_mov_b32_e32 v100, v0
	v_mov_b32_e32 v101, v0
	v_mov_b32_e32 v102, v0
	v_mov_b32_e32 v103, v0
	v_mov_b32_e32 v112, v0
	v_mov_b32_e32 v113, v0
	v_mov_b32_e32 v114, v0
	v_mov_b32_e32 v115, v0
	v_mov_b32_e32 v116, v0
	v_mov_b32_e32 v117, v0
	v_mov_b32_e32 v118, v0
	v_mov_b32_e32 v119, v0
	v_mov_b32_e32 v72, v0
	v_mov_b32_e32 v73, v0
	v_mov_b32_e32 v74, v0
	v_mov_b32_e32 v75, v0
	v_mov_b32_e32 v76, v0
	v_mov_b32_e32 v77, v0
	v_mov_b32_e32 v78, v0
	v_mov_b32_e32 v79, v0
	v_mov_b32_e32 v88, v0
	v_mov_b32_e32 v89, v0
	v_mov_b32_e32 v90, v0
	v_mov_b32_e32 v91, v0
	v_mov_b32_e32 v92, v0
	v_mov_b32_e32 v93, v0
	v_mov_b32_e32 v94, v0
	v_mov_b32_e32 v95, v0
	v_mov_b32_e32 v104, v0
	v_mov_b32_e32 v105, v0
	v_mov_b32_e32 v106, v0
	v_mov_b32_e32 v107, v0
	v_mov_b32_e32 v108, v0
	v_mov_b32_e32 v109, v0
	v_mov_b32_e32 v110, v0
	v_mov_b32_e32 v111, v0
	v_mov_b32_e32 v120, v0
	v_mov_b32_e32 v121, v0
	v_mov_b32_e32 v122, v0
	v_mov_b32_e32 v123, v0
	v_mov_b32_e32 v124, v0
	v_mov_b32_e32 v125, v0
	v_mov_b32_e32 v126, v0
	v_mov_b32_e32 v127, v0
	s_cmp_eq_u32 s19, 1
	s_cbranch_scc0 .LBB0_498
	s_mov_b32 s19, 0
	s_add_u32 s4, s26, 0xfffc0080
	s_addc_u32 s5, s27, -1
	s_add_i32 s70, 0, 0x10000
	s_cmp_eq_u32 s69, 12
	s_cselect_b32 s47, s35, s5
	s_cselect_b32 s46, s43, s4
	s_cselect_b32 s5, s31, s68
	s_cselect_b32 s4, vcc_lo, vcc_hi
	s_add_i32 s72, 0, 0x14000
	v_add_u32_e32 v150, s70, v159
	v_add_u32_e32 v170, s72, v159
	ds_read_b128 v[128:131], v150
	ds_read_b128 v[132:135], v150 offset:1024
	ds_read_b128 v[146:149], v150 offset:2048
	ds_read_b128 v[150:153], v150 offset:3072
	ds_read_b128 v[154:157], v170
	ds_read_b128 v[162:165], v170 offset:1024
	ds_read_b128 v[166:169], v170 offset:2048
	ds_read_b128 v[170:173], v170 offset:3072
	v_lshl_add_u64 v[190:191], s[26:27], 0, v[142:143]
	s_add_i32 m0, s51, 0xc000
	ds_read_b128 v[174:177], v161
	ds_read_b128 v[178:181], v161 offset:1024
	ds_read_b128 v[182:185], v161 offset:2048
	ds_read_b128 v[186:189], v161 offset:3072
	ds_read_b128 v[208:211], v161 offset:4096
	ds_read_b128 v[212:215], v161 offset:5120
	ds_read_b128 v[216:219], v161 offset:6144
	ds_read_b128 v[220:223], v161 offset:7168
	global_load_lds_dwordx4 v[190:191], off
	v_lshl_add_u64 v[190:191], s[26:27], 0, v[144:145]
	s_add_i32 m0, s51, 0xe000
	s_nop 0
	global_load_lds_dwordx4 v[190:191], off
	s_waitcnt vmcnt(24)
	s_waitcnt lgkmcnt(0)
	s_barrier
	s_setprio 1
	s_waitcnt lgkmcnt(0)
	v_mfma_f32_16x16x32_bf16 v[124:127], v[128:131], v[174:177], v[124:127]
	v_mfma_f32_16x16x32_bf16 v[120:123], v[146:149], v[174:177], v[120:123]
	v_mfma_f32_16x16x32_bf16 v[108:111], v[128:131], v[182:185], v[108:111]
	v_mfma_f32_16x16x32_bf16 v[104:107], v[146:149], v[182:185], v[104:107]
	v_mfma_f32_16x16x32_bf16 v[92:95], v[128:131], v[208:211], v[92:95]
	v_mfma_f32_16x16x32_bf16 v[88:91], v[146:149], v[208:211], v[88:91]
	v_mfma_f32_16x16x32_bf16 v[76:79], v[128:131], v[216:219], v[76:79]
	v_mfma_f32_16x16x32_bf16 v[72:75], v[146:149], v[216:219], v[72:75]
	v_mfma_f32_16x16x32_bf16 v[124:127], v[132:135], v[178:181], v[124:127]
	v_mfma_f32_16x16x32_bf16 v[120:123], v[150:153], v[178:181], v[120:123]
	v_mfma_f32_16x16x32_bf16 v[108:111], v[132:135], v[186:189], v[108:111]
	v_mfma_f32_16x16x32_bf16 v[104:107], v[150:153], v[186:189], v[104:107]
	v_mfma_f32_16x16x32_bf16 v[92:95], v[132:135], v[212:215], v[92:95]
	v_mfma_f32_16x16x32_bf16 v[88:91], v[150:153], v[212:215], v[88:91]
	v_mfma_f32_16x16x32_bf16 v[76:79], v[132:135], v[220:223], v[76:79]
	v_mfma_f32_16x16x32_bf16 v[72:75], v[150:153], v[220:223], v[72:75]
	s_setprio 0
	s_setprio 1
	v_mfma_f32_16x16x32_bf16 v[116:119], v[154:157], v[174:177], v[116:119]
	v_mfma_f32_16x16x32_bf16 v[112:115], v[166:169], v[174:177], v[112:115]
	v_mfma_f32_16x16x32_bf16 v[100:103], v[154:157], v[182:185], v[100:103]
	v_mfma_f32_16x16x32_bf16 v[96:99], v[166:169], v[182:185], v[96:99]
	v_mfma_f32_16x16x32_bf16 v[84:87], v[154:157], v[208:211], v[84:87]
	v_mfma_f32_16x16x32_bf16 v[80:83], v[166:169], v[208:211], v[80:83]
	v_mfma_f32_16x16x32_bf16 v[68:71], v[154:157], v[216:219], v[68:71]
	v_mfma_f32_16x16x32_bf16 v[64:67], v[166:169], v[216:219], v[64:67]
	v_mfma_f32_16x16x32_bf16 v[116:119], v[162:165], v[178:181], v[116:119]
	v_mfma_f32_16x16x32_bf16 v[112:115], v[170:173], v[178:181], v[112:115]
	v_mfma_f32_16x16x32_bf16 v[100:103], v[162:165], v[186:189], v[100:103]
	v_mfma_f32_16x16x32_bf16 v[96:99], v[170:173], v[186:189], v[96:99]
	v_mfma_f32_16x16x32_bf16 v[84:87], v[162:165], v[212:215], v[84:87]
	v_mfma_f32_16x16x32_bf16 v[80:83], v[170:173], v[212:215], v[80:83]
	v_mfma_f32_16x16x32_bf16 v[68:71], v[162:165], v[220:223], v[68:71]
	v_mfma_f32_16x16x32_bf16 v[64:67], v[170:173], v[220:223], v[64:67]
	s_setprio 0
	s_barrier
	s_add_i32 s70, s70, s93
	v_lshl_add_u64 v[190:191], s[4:5], 0, v[192:193]
	s_mov_b32 m0, s70
	ds_read_b128 v[174:177], v161 offset:16384
	ds_read_b128 v[178:181], v161 offset:17408
	ds_read_b128 v[182:185], v161 offset:18432
	ds_read_b128 v[186:189], v161 offset:19456
	ds_read_b128 v[208:211], v161 offset:20480
	ds_read_b128 v[212:215], v161 offset:21504
	ds_read_b128 v[216:219], v161 offset:22528
	ds_read_b128 v[220:223], v161 offset:23552
	global_load_lds_dwordx4 v[190:191], off
	s_add_i32 m0, s70, 0x2000
	s_add_u32 s70, s4, 0x40000
	v_lshl_add_u64 v[224:225], s[4:5], 0, v[140:141]
	s_addc_u32 s71, s5, 0
	s_add_i32 s72, s72, s93
	global_load_lds_dwordx4 v[224:225], off
	v_lshl_add_u64 v[226:227], s[70:71], 0, v[192:193]
	s_mov_b32 m0, s72
	v_lshl_add_u64 v[228:229], s[46:47], 0, v[138:139]
	global_load_lds_dwordx4 v[226:227], off
	v_lshl_add_u64 v[226:227], s[70:71], 0, v[140:141]
	s_add_i32 m0, s72, 0x2000
	s_nop 0
	global_load_lds_dwordx4 v[226:227], off
	v_lshl_add_u64 v[226:227], s[46:47], 0, v[136:137]
	s_mov_b32 m0, s51
	s_nop 0
	global_load_lds_dwordx4 v[226:227], off
	s_mov_b32 m0, s94
	s_nop 0
	global_load_lds_dwordx4 v[228:229], off
	s_waitcnt vmcnt(24)
	s_branch .Lpeel_mid_inb

.Lpeel_mid_inb:
	s_waitcnt lgkmcnt(0)
	s_barrier
	s_setprio 1
	s_waitcnt lgkmcnt(0)
	v_mfma_f32_16x16x32_bf16 v[60:63], v[128:131], v[174:177], v[60:63]
	v_mfma_f32_16x16x32_bf16 v[56:59], v[146:149], v[174:177], v[56:59]
	v_mfma_f32_16x16x32_bf16 v[44:47], v[128:131], v[182:185], v[44:47]
	v_mfma_f32_16x16x32_bf16 v[40:43], v[146:149], v[182:185], v[40:43]
	v_mfma_f32_16x16x32_bf16 v[28:31], v[128:131], v[208:211], v[28:31]
	v_mfma_f32_16x16x32_bf16 v[24:27], v[146:149], v[208:211], v[24:27]
	v_mfma_f32_16x16x32_bf16 v[12:15], v[128:131], v[216:219], v[12:15]
	v_mfma_f32_16x16x32_bf16 v[8:11], v[146:149], v[216:219], v[8:11]
	v_mfma_f32_16x16x32_bf16 v[60:63], v[132:135], v[178:181], v[60:63]
	v_mfma_f32_16x16x32_bf16 v[56:59], v[150:153], v[178:181], v[56:59]
	v_mfma_f32_16x16x32_bf16 v[44:47], v[132:135], v[186:189], v[44:47]
	v_mfma_f32_16x16x32_bf16 v[40:43], v[150:153], v[186:189], v[40:43]
	v_mfma_f32_16x16x32_bf16 v[28:31], v[132:135], v[212:215], v[28:31]
	v_mfma_f32_16x16x32_bf16 v[24:27], v[150:153], v[212:215], v[24:27]
	v_mfma_f32_16x16x32_bf16 v[12:15], v[132:135], v[220:223], v[12:15]
	v_mfma_f32_16x16x32_bf16 v[8:11], v[150:153], v[220:223], v[8:11]
	s_setprio 0
	s_setprio 1
	v_mfma_f32_16x16x32_bf16 v[52:55], v[154:157], v[174:177], v[52:55]
	v_mfma_f32_16x16x32_bf16 v[48:51], v[166:169], v[174:177], v[48:51]
	v_mfma_f32_16x16x32_bf16 v[36:39], v[154:157], v[182:185], v[36:39]
	v_mfma_f32_16x16x32_bf16 v[32:35], v[166:169], v[182:185], v[32:35]
	v_mfma_f32_16x16x32_bf16 v[20:23], v[154:157], v[208:211], v[20:23]
	v_mfma_f32_16x16x32_bf16 v[16:19], v[166:169], v[208:211], v[16:19]
	v_mfma_f32_16x16x32_bf16 v[4:7], v[154:157], v[216:219], v[4:7]
	v_mfma_f32_16x16x32_bf16 v[0:3], v[166:169], v[216:219], v[0:3]
	v_mfma_f32_16x16x32_bf16 v[52:55], v[162:165], v[178:181], v[52:55]
	v_mfma_f32_16x16x32_bf16 v[48:51], v[170:173], v[178:181], v[48:51]
	v_mfma_f32_16x16x32_bf16 v[36:39], v[162:165], v[186:189], v[36:39]
	v_mfma_f32_16x16x32_bf16 v[32:35], v[170:173], v[186:189], v[32:35]
	v_mfma_f32_16x16x32_bf16 v[20:23], v[162:165], v[212:215], v[20:23]
	v_mfma_f32_16x16x32_bf16 v[16:19], v[170:173], v[212:215], v[16:19]
	v_mfma_f32_16x16x32_bf16 v[4:7], v[162:165], v[220:223], v[4:7]
	v_mfma_f32_16x16x32_bf16 v[0:3], v[170:173], v[220:223], v[0:3]
	s_setprio 0
	s_barrier
	s_add_i32 s70, 0, 0x18000
	s_add_i32 s71, 0, 0x1c000
	v_add_u32_e32 v150, s70, v159
	v_add_u32_e32 v170, s71, v159
	ds_read_b128 v[128:131], v150
	ds_read_b128 v[132:135], v150 offset:1024
	ds_read_b128 v[146:149], v150 offset:2048
	ds_read_b128 v[150:153], v150 offset:3072
	ds_read_b128 v[154:157], v170
	ds_read_b128 v[162:165], v170 offset:1024
	ds_read_b128 v[166:169], v170 offset:2048
	ds_read_b128 v[170:173], v170 offset:3072
	s_add_u32 s46, s46, 0x40000
	s_addc_u32 s47, s47, 0
	s_mov_b32 m0, s95
	v_lshl_add_u64 v[230:231], s[46:47], 0, v[136:137]
	ds_read_b128 v[174:177], v161 offset:32768
	ds_read_b128 v[178:181], v161 offset:33792
	ds_read_b128 v[182:185], v161 offset:34816
	ds_read_b128 v[186:189], v161 offset:35840
	ds_read_b128 v[208:211], v161 offset:36864
	ds_read_b128 v[212:215], v161 offset:37888
	ds_read_b128 v[216:219], v161 offset:38912
	ds_read_b128 v[220:223], v161 offset:39936
	global_load_lds_dwordx4 v[230:231], off
	v_lshl_add_u64 v[230:231], s[46:47], 0, v[138:139]
	s_mov_b32 m0, s96
	s_nop 0
	global_load_lds_dwordx4 v[230:231], off
	s_waitcnt vmcnt(8)
	s_waitcnt lgkmcnt(0)
	s_barrier
	s_setprio 1
	s_waitcnt lgkmcnt(0)
	v_mfma_f32_16x16x32_bf16 v[124:127], v[128:131], v[174:177], v[124:127]
	v_mfma_f32_16x16x32_bf16 v[120:123], v[146:149], v[174:177], v[120:123]
	v_mfma_f32_16x16x32_bf16 v[108:111], v[128:131], v[182:185], v[108:111]
	v_mfma_f32_16x16x32_bf16 v[104:107], v[146:149], v[182:185], v[104:107]
	v_mfma_f32_16x16x32_bf16 v[92:95], v[128:131], v[208:211], v[92:95]
	v_mfma_f32_16x16x32_bf16 v[88:91], v[146:149], v[208:211], v[88:91]
	v_mfma_f32_16x16x32_bf16 v[76:79], v[128:131], v[216:219], v[76:79]
	v_mfma_f32_16x16x32_bf16 v[72:75], v[146:149], v[216:219], v[72:75]
	v_mfma_f32_16x16x32_bf16 v[124:127], v[132:135], v[178:181], v[124:127]
	v_mfma_f32_16x16x32_bf16 v[120:123], v[150:153], v[178:181], v[120:123]
	v_mfma_f32_16x16x32_bf16 v[108:111], v[132:135], v[186:189], v[108:111]
	v_mfma_f32_16x16x32_bf16 v[104:107], v[150:153], v[186:189], v[104:107]
	v_mfma_f32_16x16x32_bf16 v[92:95], v[132:135], v[212:215], v[92:95]
	v_mfma_f32_16x16x32_bf16 v[88:91], v[150:153], v[212:215], v[88:91]
	v_mfma_f32_16x16x32_bf16 v[76:79], v[132:135], v[220:223], v[76:79]
	v_mfma_f32_16x16x32_bf16 v[72:75], v[150:153], v[220:223], v[72:75]
	s_setprio 0
	s_setprio 1
	v_mfma_f32_16x16x32_bf16 v[116:119], v[154:157], v[174:177], v[116:119]
	v_mfma_f32_16x16x32_bf16 v[112:115], v[166:169], v[174:177], v[112:115]
	v_mfma_f32_16x16x32_bf16 v[100:103], v[154:157], v[182:185], v[100:103]
	v_mfma_f32_16x16x32_bf16 v[96:99], v[166:169], v[182:185], v[96:99]
	v_mfma_f32_16x16x32_bf16 v[84:87], v[154:157], v[208:211], v[84:87]
	v_mfma_f32_16x16x32_bf16 v[80:83], v[166:169], v[208:211], v[80:83]
	v_mfma_f32_16x16x32_bf16 v[68:71], v[154:157], v[216:219], v[68:71]
	v_mfma_f32_16x16x32_bf16 v[64:67], v[166:169], v[216:219], v[64:67]
	v_mfma_f32_16x16x32_bf16 v[116:119], v[162:165], v[178:181], v[116:119]
	v_mfma_f32_16x16x32_bf16 v[112:115], v[170:173], v[178:181], v[112:115]
	v_mfma_f32_16x16x32_bf16 v[100:103], v[162:165], v[186:189], v[100:103]
	v_mfma_f32_16x16x32_bf16 v[96:99], v[170:173], v[186:189], v[96:99]
	v_mfma_f32_16x16x32_bf16 v[84:87], v[162:165], v[212:215], v[84:87]
	v_mfma_f32_16x16x32_bf16 v[80:83], v[170:173], v[212:215], v[80:83]
	v_mfma_f32_16x16x32_bf16 v[68:71], v[162:165], v[220:223], v[68:71]
	v_mfma_f32_16x16x32_bf16 v[64:67], v[170:173], v[220:223], v[64:67]
	s_setprio 0
	s_barrier
	s_add_i32 s46, s70, s93
	v_lshl_add_u64 v[190:191], v[190:191], 0, s[8:9]
	s_mov_b32 m0, s46
	ds_read_b128 v[174:177], v161 offset:49152
	ds_read_b128 v[178:181], v161 offset:50176
	ds_read_b128 v[182:185], v161 offset:51200
	ds_read_b128 v[186:189], v161 offset:52224
	ds_read_b128 v[208:211], v161 offset:53248
	ds_read_b128 v[212:215], v161 offset:54272
	ds_read_b128 v[216:219], v161 offset:55296
	ds_read_b128 v[220:223], v161 offset:56320
	global_load_lds_dwordx4 v[190:191], off
	s_add_i32 m0, s46, 0x2000
	s_add_u32 s4, s4, 0x40080
	v_lshl_add_u64 v[190:191], v[224:225], 0, s[8:9]
	s_addc_u32 s5, s5, 0
	s_add_i32 s46, s71, s93
	global_load_lds_dwordx4 v[190:191], off
	v_lshl_add_u64 v[190:191], s[4:5], 0, v[192:193]
	s_mov_b32 m0, s46
	s_nop 0
	global_load_lds_dwordx4 v[190:191], off
	v_lshl_add_u64 v[190:191], s[4:5], 0, v[140:141]
	s_add_i32 m0, s46, 0x2000
	s_nop 0
	global_load_lds_dwordx4 v[190:191], off
	v_lshl_add_u64 v[190:191], v[226:227], 0, s[8:9]
	s_mov_b32 m0, s63
	s_nop 0
	global_load_lds_dwordx4 v[190:191], off
	v_lshl_add_u64 v[190:191], v[228:229], 0, s[8:9]
	s_mov_b32 m0, s64
	s_nop 0
	global_load_lds_dwordx4 v[190:191], off
	s_waitcnt vmcnt(8)
	s_waitcnt lgkmcnt(0)
	s_barrier
	s_setprio 1
	s_waitcnt lgkmcnt(0)
	v_mfma_f32_16x16x32_bf16 v[60:63], v[128:131], v[174:177], v[60:63]
	v_mfma_f32_16x16x32_bf16 v[56:59], v[146:149], v[174:177], v[56:59]
	v_mfma_f32_16x16x32_bf16 v[44:47], v[128:131], v[182:185], v[44:47]
	v_mfma_f32_16x16x32_bf16 v[40:43], v[146:149], v[182:185], v[40:43]
	v_mfma_f32_16x16x32_bf16 v[28:31], v[128:131], v[208:211], v[28:31]
	v_mfma_f32_16x16x32_bf16 v[24:27], v[146:149], v[208:211], v[24:27]
	v_mfma_f32_16x16x32_bf16 v[12:15], v[128:131], v[216:219], v[12:15]
	v_mfma_f32_16x16x32_bf16 v[8:11], v[146:149], v[216:219], v[8:11]
	v_mfma_f32_16x16x32_bf16 v[60:63], v[132:135], v[178:181], v[60:63]
	v_mfma_f32_16x16x32_bf16 v[56:59], v[150:153], v[178:181], v[56:59]
	v_mfma_f32_16x16x32_bf16 v[44:47], v[132:135], v[186:189], v[44:47]
	v_mfma_f32_16x16x32_bf16 v[40:43], v[150:153], v[186:189], v[40:43]
	v_mfma_f32_16x16x32_bf16 v[28:31], v[132:135], v[212:215], v[28:31]
	v_mfma_f32_16x16x32_bf16 v[24:27], v[150:153], v[212:215], v[24:27]
	v_mfma_f32_16x16x32_bf16 v[12:15], v[132:135], v[220:223], v[12:15]
	v_mfma_f32_16x16x32_bf16 v[8:11], v[150:153], v[220:223], v[8:11]
	s_setprio 0
	s_setprio 1
	v_mfma_f32_16x16x32_bf16 v[52:55], v[154:157], v[174:177], v[52:55]
	v_mfma_f32_16x16x32_bf16 v[48:51], v[166:169], v[174:177], v[48:51]
	v_mfma_f32_16x16x32_bf16 v[36:39], v[154:157], v[182:185], v[36:39]
	v_mfma_f32_16x16x32_bf16 v[32:35], v[166:169], v[182:185], v[32:35]
	v_mfma_f32_16x16x32_bf16 v[20:23], v[154:157], v[208:211], v[20:23]
	v_mfma_f32_16x16x32_bf16 v[16:19], v[166:169], v[208:211], v[16:19]
	v_mfma_f32_16x16x32_bf16 v[4:7], v[154:157], v[216:219], v[4:7]
	v_mfma_f32_16x16x32_bf16 v[0:3], v[166:169], v[216:219], v[0:3]
	v_mfma_f32_16x16x32_bf16 v[52:55], v[162:165], v[178:181], v[52:55]
	v_mfma_f32_16x16x32_bf16 v[48:51], v[170:173], v[178:181], v[48:51]
	v_mfma_f32_16x16x32_bf16 v[36:39], v[162:165], v[186:189], v[36:39]
	v_mfma_f32_16x16x32_bf16 v[32:35], v[170:173], v[186:189], v[32:35]
	v_mfma_f32_16x16x32_bf16 v[20:23], v[162:165], v[212:215], v[20:23]
	v_mfma_f32_16x16x32_bf16 v[16:19], v[170:173], v[212:215], v[16:19]
	v_mfma_f32_16x16x32_bf16 v[4:7], v[162:165], v[220:223], v[4:7]
	v_mfma_f32_16x16x32_bf16 v[0:3], v[170:173], v[220:223], v[0:3]
	s_setprio 0
	s_barrier
	s_add_i32 s69, s69, 2
	s_add_u32 s26, s26, 0x100
	s_addc_u32 s27, s27, 0
	s_add_u32 vcc_hi, vcc_hi, 0x100
	s_addc_u32 s68, s68, 0
	s_cmp_gt_u32 s69, 13
	s_cbranch_scc0 .LBB0_498
	s_and_b64 vcc, exec, s[16:17]
	s_cbranch_vccz .LBB0_501
	s_barrier

.Linb_done:
	s_mov_b32 s19, 1
	s_andn2_b64 vcc, exec, s[36:37]
	s_mov_b64 s[4:5], -1
	s_branch .Linb_tail
